# FoX forget-gate logits (fl_rows): wave sums via DPP/permlane ladders instead of six serialised ds_bpermute round trips per weight row
# speedup vs baseline: 1.0039x; 1.0022x over previous
; #define LAS __attribute__((address_space(3)))
; __device__ __forceinline__ void fl_rows(CPR P, LAS unsigned char* lds) {
;     ...
;     for (int row = blockIdx.x * 8 + wave; row < S; row += gridDim.x * 8) {
;         float xv[32];
; #pragma unroll
;         for (int q = 0; q < 4; ++q) {
;             const u32x4 v = *(const u32x4*)(xb + (size_t)row * DM + lane * 32 + q * 8);
; #pragma unroll
;             for (int e = 0; e < 4; ++e) { xv[q * 8 + 2 * e] = __uint_as_float(v[e] << 16); xv[q * 8 + 2 * e + 1] = __uint_as_float(v[e] & 0xffff0000u); }
;         }
;         float acc[8];
; #pragma unroll
;         for (int j = 0; j < 8; ++j) {
;             float a = 0.f;
; #pragma unroll
;             for (int q = 0; q < 4; ++q) {
;                 const u32x4 w = *(const LAS u32x4*)(lds + j * 4096 + lane * 64 + q * 16);
; #pragma unroll
;                 for (int e = 0; e < 4; ++e) { a += xv[q * 8 + 2 * e] * __uint_as_float(w[e] << 16); a += xv[q * 8 + 2 * e + 1] * __uint_as_float(w[e] & 0xffff0000u); }
;             }
;             acc[j] = wsum(a);
;             __builtin_amdgcn_sched_barrier(0);
.LBB0_823:
	v_ashrrev_i32_e32 v3, 31, v2
	s_waitcnt lgkmcnt(0)
	v_lshlrev_b64 v[14:15], 12, v[2:3]
	v_lshl_add_u64 v[22:23], v[4:5], 0, v[14:15]
	global_load_dwordx4 v[14:17], v[22:23], off
	global_load_dwordx4 v[18:21], v[22:23], off offset:16
	global_load_dwordx4 v[48:51], v[22:23], off offset:32
	global_load_dwordx4 v[52:55], v[22:23], off offset:48
	ds_read_b128 v[22:25], v13
	ds_read_b128 v[26:29], v13 offset:16
	ds_read_b128 v[30:33], v13 offset:32
	ds_read_b128 v[56:59], v13 offset:48
	s_waitcnt lgkmcnt(3)
	v_lshlrev_b32_e32 v60, 16, v22
	v_and_b32_e32 v22, 0xffff0000, v22
	s_waitcnt lgkmcnt(1)
	v_lshlrev_b32_e32 v74, 16, v30
	v_and_b32_e32 v75, 0xffff0000, v30
	v_lshlrev_b32_e32 v76, 16, v31
	v_and_b32_e32 v77, 0xffff0000, v31
	v_lshlrev_b32_e32 v61, 16, v23
	v_and_b32_e32 v62, 0xffff0000, v23
	v_lshlrev_b32_e32 v63, 16, v24
	v_and_b32_e32 v24, 0xffff0000, v24
	v_lshlrev_b32_e32 v64, 16, v25
	v_and_b32_e32 v65, 0xffff0000, v25
	v_lshlrev_b32_e32 v66, 16, v26
	v_and_b32_e32 v67, 0xffff0000, v26
	v_lshlrev_b32_e32 v68, 16, v27
	v_and_b32_e32 v69, 0xffff0000, v27
	v_lshlrev_b32_e32 v70, 16, v28
	v_and_b32_e32 v71, 0xffff0000, v28
	v_lshlrev_b32_e32 v72, 16, v29
	v_lshlrev_b32_e32 v80, 16, v33
	v_and_b32_e32 v81, 0xffff0000, v33
	v_and_b32_e32 v73, 0xffff0000, v29
	v_lshlrev_b32_e32 v78, 16, v32
	v_and_b32_e32 v79, 0xffff0000, v32
	s_waitcnt lgkmcnt(0)
	v_lshlrev_b32_e32 v82, 16, v56
	v_and_b32_e32 v56, 0xffff0000, v56
	v_lshlrev_b32_e32 v83, 16, v57
	v_and_b32_e32 v57, 0xffff0000, v57
	v_lshlrev_b32_e32 v84, 16, v58
	v_and_b32_e32 v58, 0xffff0000, v58
	v_lshlrev_b32_e32 v85, 16, v59
	s_waitcnt vmcnt(3)
	v_lshlrev_b32_e32 v47, 16, v14
	v_and_b32_e32 v46, 0xffff0000, v14
	s_waitcnt vmcnt(1)
	v_lshlrev_b32_e32 v31, 16, v48
	v_and_b32_e32 v30, 0xffff0000, v48
	v_fma_f32 v48, v47, v60, 0
	v_lshlrev_b32_e32 v45, 16, v15
	v_fmac_f32_e32 v48, v46, v22
	v_and_b32_e32 v44, 0xffff0000, v15
	v_fmac_f32_e32 v48, v45, v61
	v_lshlrev_b32_e32 v43, 16, v16
	v_fmac_f32_e32 v48, v44, v62
	v_and_b32_e32 v42, 0xffff0000, v16
	v_fmac_f32_e32 v48, v43, v63
	v_lshlrev_b32_e32 v41, 16, v17
	v_fmac_f32_e32 v48, v42, v24
	v_and_b32_e32 v40, 0xffff0000, v17
	v_fmac_f32_e32 v48, v41, v64
	v_lshlrev_b32_e32 v39, 16, v18
	v_fmac_f32_e32 v48, v40, v65
	v_and_b32_e32 v38, 0xffff0000, v18
	v_fmac_f32_e32 v48, v39, v66
	v_lshlrev_b32_e32 v37, 16, v19
	v_fmac_f32_e32 v48, v38, v67
	v_and_b32_e32 v36, 0xffff0000, v19
	v_fmac_f32_e32 v48, v37, v68
	v_lshlrev_b32_e32 v35, 16, v20
	v_fmac_f32_e32 v48, v36, v69
	v_and_b32_e32 v34, 0xffff0000, v20
	v_fmac_f32_e32 v48, v35, v70
	v_lshlrev_b32_e32 v33, 16, v21
	v_fmac_f32_e32 v48, v34, v71
	v_and_b32_e32 v32, 0xffff0000, v21
	v_fmac_f32_e32 v48, v33, v72
	v_fmac_f32_e32 v48, v32, v73
	v_fmac_f32_e32 v48, v31, v74
	v_lshlrev_b32_e32 v29, 16, v49
	v_fmac_f32_e32 v48, v30, v75
	v_and_b32_e32 v28, 0xffff0000, v49
	v_fmac_f32_e32 v48, v29, v76
	v_lshlrev_b32_e32 v27, 16, v50
	v_fmac_f32_e32 v48, v28, v77
	v_and_b32_e32 v26, 0xffff0000, v50
	v_fmac_f32_e32 v48, v27, v78
	v_lshlrev_b32_e32 v25, 16, v51
	v_fmac_f32_e32 v48, v26, v79
	v_and_b32_e32 v23, 0xffff0000, v51
	v_fmac_f32_e32 v48, v25, v80
	s_waitcnt vmcnt(0)
	v_lshlrev_b32_e32 v21, 16, v52
	v_fmac_f32_e32 v48, v23, v81
	v_and_b32_e32 v20, 0xffff0000, v52
	v_fmac_f32_e32 v48, v21, v82
	v_lshlrev_b32_e32 v19, 16, v53
	v_fmac_f32_e32 v48, v20, v56
	v_and_b32_e32 v18, 0xffff0000, v53
	v_fmac_f32_e32 v48, v19, v83
	v_lshlrev_b32_e32 v17, 16, v54
	v_fmac_f32_e32 v48, v18, v57
	v_and_b32_e32 v16, 0xffff0000, v54
	v_fmac_f32_e32 v48, v17, v84
	v_lshlrev_b32_e32 v15, 16, v55
	v_fmac_f32_e32 v48, v16, v58
	v_and_b32_e32 v14, 0xffff0000, v55
	v_fmac_f32_e32 v48, v15, v85
	v_and_b32_e32 v22, 0xffff0000, v59
	v_fmac_f32_e32 v48, v14, v22
	s_nop 1
	v_add_f32_dpp v22, v48, v48 quad_perm:[1,0,3,2] row_mask:0xf bank_mask:0xf
	s_nop 1
	v_add_f32_dpp v24, v22, v22 quad_perm:[2,3,0,1] row_mask:0xf bank_mask:0xf
	s_nop 1
	v_add_f32_dpp v22, v24, v24 row_half_mirror row_mask:0xf bank_mask:0xf
	s_nop 1
	v_add_f32_dpp v24, v22, v22 row_mirror row_mask:0xf bank_mask:0xf
	v_mov_b32_e32 v22, v24
	s_nop 1
	v_permlane16_swap_b32_e32 v24, v22
	v_add_f32_e32 v24, v24, v22
	v_mov_b32_e32 v22, v24
	s_nop 1
	v_permlane32_swap_b32_e32 v24, v22
	ds_read_b128 v[48:51], v13 offset:4096
	ds_read_b128 v[52:55], v13 offset:4112
	ds_read_b128 v[56:59], v13 offset:4128
	ds_read_b128 v[60:63], v13 offset:4144
	s_waitcnt lgkmcnt(3)
	v_lshlrev_b32_e32 v64, 16, v48
	v_and_b32_e32 v48, 0xffff0000, v48
	v_fma_f32 v64, v47, v64, 0
	v_fmac_f32_e32 v64, v46, v48
	v_lshlrev_b32_e32 v48, 16, v49
	v_fmac_f32_e32 v64, v45, v48
	v_and_b32_e32 v48, 0xffff0000, v49
	v_fmac_f32_e32 v64, v44, v48
	v_lshlrev_b32_e32 v48, 16, v50
	v_fmac_f32_e32 v64, v43, v48
	v_and_b32_e32 v48, 0xffff0000, v50
	v_fmac_f32_e32 v64, v42, v48
	v_lshlrev_b32_e32 v48, 16, v51
	v_fmac_f32_e32 v64, v41, v48
	v_and_b32_e32 v48, 0xffff0000, v51
	v_fmac_f32_e32 v64, v40, v48
	s_waitcnt lgkmcnt(2)
	v_lshlrev_b32_e32 v48, 16, v52
	v_fmac_f32_e32 v64, v39, v48
	v_and_b32_e32 v48, 0xffff0000, v52
	v_fmac_f32_e32 v64, v38, v48
	v_lshlrev_b32_e32 v48, 16, v53
	v_fmac_f32_e32 v64, v37, v48
	v_and_b32_e32 v48, 0xffff0000, v53
	v_fmac_f32_e32 v64, v36, v48
	v_lshlrev_b32_e32 v48, 16, v54
	v_fmac_f32_e32 v64, v35, v48
	v_and_b32_e32 v48, 0xffff0000, v54
	v_fmac_f32_e32 v64, v34, v48
	v_lshlrev_b32_e32 v48, 16, v55
	v_fmac_f32_e32 v64, v33, v48
	v_and_b32_e32 v48, 0xffff0000, v55
	v_fmac_f32_e32 v64, v32, v48
	s_waitcnt lgkmcnt(1)
; #define LAS __attribute__((address_space(3)))
; __device__ __forceinline__ void fl_rows(CPR P, LAS unsigned char* lds) {
;     ...
;         for (int j = 0; j < 8; ++j) {
;             float a = 0.f;
; #pragma unroll
;             for (int q = 0; q < 4; ++q) {
;                 const u32x4 w = *(const LAS u32x4*)(lds + j * 4096 + lane * 64 + q * 16);
; #pragma unroll
;                 for (int e = 0; e < 4; ++e) { a += xv[q * 8 + 2 * e] * __uint_as_float(w[e] << 16); a += xv[q * 8 + 2 * e + 1] * __uint_as_float(w[e] & 0xffff0000u); }
;             }
;             acc[j] = wsum(a);
;             __builtin_amdgcn_sched_barrier(0);
	v_lshlrev_b32_e32 v48, 16, v56
	v_fmac_f32_e32 v64, v31, v48
	v_and_b32_e32 v48, 0xffff0000, v56
	v_fmac_f32_e32 v64, v30, v48
	v_lshlrev_b32_e32 v48, 16, v57
	v_fmac_f32_e32 v64, v29, v48
	v_and_b32_e32 v48, 0xffff0000, v57
	v_fmac_f32_e32 v64, v28, v48
	v_lshlrev_b32_e32 v48, 16, v58
	v_fmac_f32_e32 v64, v27, v48
	v_and_b32_e32 v48, 0xffff0000, v58
	v_fmac_f32_e32 v64, v26, v48
	v_lshlrev_b32_e32 v48, 16, v59
	v_fmac_f32_e32 v64, v25, v48
	v_and_b32_e32 v48, 0xffff0000, v59
	v_fmac_f32_e32 v64, v23, v48
	s_waitcnt lgkmcnt(0)
	v_lshlrev_b32_e32 v48, 16, v60
	v_fmac_f32_e32 v64, v21, v48
	v_and_b32_e32 v48, 0xffff0000, v60
	v_fmac_f32_e32 v64, v20, v48
	v_lshlrev_b32_e32 v48, 16, v61
	v_fmac_f32_e32 v64, v19, v48
	v_and_b32_e32 v48, 0xffff0000, v61
	v_fmac_f32_e32 v64, v18, v48
	v_lshlrev_b32_e32 v48, 16, v62
	v_fmac_f32_e32 v64, v17, v48
	v_and_b32_e32 v48, 0xffff0000, v62
	v_fmac_f32_e32 v64, v16, v48
	v_lshlrev_b32_e32 v48, 16, v63
	v_fmac_f32_e32 v64, v15, v48
	v_and_b32_e32 v48, 0xffff0000, v63
	v_fmac_f32_e32 v64, v14, v48
	s_nop 1
	v_add_f32_dpp v48, v64, v64 quad_perm:[1,0,3,2] row_mask:0xf bank_mask:0xf
	s_nop 1
	v_add_f32_dpp v49, v48, v48 quad_perm:[2,3,0,1] row_mask:0xf bank_mask:0xf
	s_nop 1
	v_add_f32_dpp v48, v49, v49 row_half_mirror row_mask:0xf bank_mask:0xf
	s_nop 1
	v_add_f32_dpp v49, v48, v48 row_mirror row_mask:0xf bank_mask:0xf
	v_mov_b32_e32 v48, v49
	s_nop 1
	v_permlane16_swap_b32_e32 v49, v48
	v_add_f32_e32 v49, v49, v48
	v_mov_b32_e32 v48, v49
	s_nop 1
	v_permlane32_swap_b32_e32 v49, v48
	ds_read_b128 v[50:53], v13 offset:8192
	ds_read_b128 v[54:57], v13 offset:8208
	ds_read_b128 v[58:61], v13 offset:8224
	ds_read_b128 v[62:65], v13 offset:8240
	s_waitcnt lgkmcnt(3)
	v_lshlrev_b32_e32 v66, 16, v50
	v_and_b32_e32 v50, 0xffff0000, v50
	v_fma_f32 v66, v47, v66, 0
	v_fmac_f32_e32 v66, v46, v50
	v_lshlrev_b32_e32 v50, 16, v51
	v_fmac_f32_e32 v66, v45, v50
	v_and_b32_e32 v50, 0xffff0000, v51
	v_fmac_f32_e32 v66, v44, v50
	v_lshlrev_b32_e32 v50, 16, v52
	v_fmac_f32_e32 v66, v43, v50
	v_and_b32_e32 v50, 0xffff0000, v52
	v_fmac_f32_e32 v66, v42, v50
	v_lshlrev_b32_e32 v50, 16, v53
	v_fmac_f32_e32 v66, v41, v50
	v_and_b32_e32 v50, 0xffff0000, v53
	v_fmac_f32_e32 v66, v40, v50
	s_waitcnt lgkmcnt(2)
	v_lshlrev_b32_e32 v50, 16, v54
	v_fmac_f32_e32 v66, v39, v50
	v_and_b32_e32 v50, 0xffff0000, v54
	v_fmac_f32_e32 v66, v38, v50
	v_lshlrev_b32_e32 v50, 16, v55
	v_fmac_f32_e32 v66, v37, v50
	v_and_b32_e32 v50, 0xffff0000, v55
	v_fmac_f32_e32 v66, v36, v50
	v_lshlrev_b32_e32 v50, 16, v56
	v_fmac_f32_e32 v66, v35, v50
	v_and_b32_e32 v50, 0xffff0000, v56
	v_fmac_f32_e32 v66, v34, v50
	v_lshlrev_b32_e32 v50, 16, v57
	v_fmac_f32_e32 v66, v33, v50
	v_and_b32_e32 v50, 0xffff0000, v57
	v_fmac_f32_e32 v66, v32, v50
	s_waitcnt lgkmcnt(1)
	v_lshlrev_b32_e32 v50, 16, v58
	v_fmac_f32_e32 v66, v31, v50
	v_and_b32_e32 v50, 0xffff0000, v58
	v_fmac_f32_e32 v66, v30, v50
	v_lshlrev_b32_e32 v50, 16, v59
	v_fmac_f32_e32 v66, v29, v50
	v_and_b32_e32 v50, 0xffff0000, v59
	v_fmac_f32_e32 v66, v28, v50
	v_lshlrev_b32_e32 v50, 16, v60
	v_fmac_f32_e32 v66, v27, v50
	v_and_b32_e32 v50, 0xffff0000, v60
	v_fmac_f32_e32 v66, v26, v50
	v_lshlrev_b32_e32 v50, 16, v61
	v_fmac_f32_e32 v66, v25, v50
	v_and_b32_e32 v50, 0xffff0000, v61
	v_fmac_f32_e32 v66, v23, v50
	s_waitcnt lgkmcnt(0)
	v_lshlrev_b32_e32 v50, 16, v62
	v_fmac_f32_e32 v66, v21, v50
	v_and_b32_e32 v50, 0xffff0000, v62
	v_fmac_f32_e32 v66, v20, v50
	v_lshlrev_b32_e32 v50, 16, v63
	v_fmac_f32_e32 v66, v19, v50
	v_and_b32_e32 v50, 0xffff0000, v63
	v_fmac_f32_e32 v66, v18, v50
	v_lshlrev_b32_e32 v50, 16, v64
	v_fmac_f32_e32 v66, v17, v50
	v_and_b32_e32 v50, 0xffff0000, v64
	v_fmac_f32_e32 v66, v16, v50
	v_lshlrev_b32_e32 v50, 16, v65
	v_fmac_f32_e32 v66, v15, v50
	v_and_b32_e32 v50, 0xffff0000, v65
	v_fmac_f32_e32 v66, v14, v50
	s_nop 1
	v_add_f32_dpp v50, v66, v66 quad_perm:[1,0,3,2] row_mask:0xf bank_mask:0xf
	s_nop 1
	v_add_f32_dpp v51, v50, v50 quad_perm:[2,3,0,1] row_mask:0xf bank_mask:0xf
	s_nop 1
	v_add_f32_dpp v50, v51, v51 row_half_mirror row_mask:0xf bank_mask:0xf
	s_nop 1
	v_add_f32_dpp v51, v50, v50 row_mirror row_mask:0xf bank_mask:0xf
	v_mov_b32_e32 v50, v51
	s_nop 1
	v_permlane16_swap_b32_e32 v51, v50
	v_add_f32_e32 v51, v51, v50
	v_mov_b32_e32 v50, v51
	s_nop 1
	v_permlane32_swap_b32_e32 v51, v50
	ds_read_b128 v[52:55], v13 offset:12288
	ds_read_b128 v[56:59], v13 offset:12304
	ds_read_b128 v[60:63], v13 offset:12320
	ds_read_b128 v[64:67], v13 offset:12336
	s_waitcnt lgkmcnt(3)
	v_lshlrev_b32_e32 v68, 16, v52
	v_and_b32_e32 v52, 0xffff0000, v52
	v_fma_f32 v68, v47, v68, 0
	v_fmac_f32_e32 v68, v46, v52
	v_lshlrev_b32_e32 v52, 16, v53
	v_fmac_f32_e32 v68, v45, v52
	v_and_b32_e32 v52, 0xffff0000, v53
	v_fmac_f32_e32 v68, v44, v52
	v_lshlrev_b32_e32 v52, 16, v54
	v_fmac_f32_e32 v68, v43, v52
	v_and_b32_e32 v52, 0xffff0000, v54
	v_fmac_f32_e32 v68, v42, v52
	v_lshlrev_b32_e32 v52, 16, v55
	v_fmac_f32_e32 v68, v41, v52
	v_and_b32_e32 v52, 0xffff0000, v55
	v_fmac_f32_e32 v68, v40, v52
	s_waitcnt lgkmcnt(2)
	v_lshlrev_b32_e32 v52, 16, v56
	v_fmac_f32_e32 v68, v39, v52
	v_and_b32_e32 v52, 0xffff0000, v56
	v_fmac_f32_e32 v68, v38, v52
	v_lshlrev_b32_e32 v52, 16, v57
	v_fmac_f32_e32 v68, v37, v52
	v_and_b32_e32 v52, 0xffff0000, v57
	v_fmac_f32_e32 v68, v36, v52
	v_lshlrev_b32_e32 v52, 16, v58
	v_fmac_f32_e32 v68, v35, v52
	v_and_b32_e32 v52, 0xffff0000, v58
	v_fmac_f32_e32 v68, v34, v52
	v_lshlrev_b32_e32 v52, 16, v59
	v_fmac_f32_e32 v68, v33, v52
	v_and_b32_e32 v52, 0xffff0000, v59
	v_fmac_f32_e32 v68, v32, v52
	s_waitcnt lgkmcnt(1)
; #define LAS __attribute__((address_space(3)))
; __device__ __forceinline__ void fl_rows(CPR P, LAS unsigned char* lds) {
;     ...
;         for (int j = 0; j < 8; ++j) {
;             float a = 0.f;
; #pragma unroll
;             for (int q = 0; q < 4; ++q) {
;                 const u32x4 w = *(const LAS u32x4*)(lds + j * 4096 + lane * 64 + q * 16);
; #pragma unroll
;                 for (int e = 0; e < 4; ++e) { a += xv[q * 8 + 2 * e] * __uint_as_float(w[e] << 16); a += xv[q * 8 + 2 * e + 1] * __uint_as_float(w[e] & 0xffff0000u); }
;             }
;             acc[j] = wsum(a);
;             __builtin_amdgcn_sched_barrier(0);
	v_lshlrev_b32_e32 v52, 16, v60
	v_fmac_f32_e32 v68, v31, v52
	v_and_b32_e32 v52, 0xffff0000, v60
	v_fmac_f32_e32 v68, v30, v52
	v_lshlrev_b32_e32 v52, 16, v61
	v_fmac_f32_e32 v68, v29, v52
	v_and_b32_e32 v52, 0xffff0000, v61
	v_fmac_f32_e32 v68, v28, v52
	v_lshlrev_b32_e32 v52, 16, v62
	v_fmac_f32_e32 v68, v27, v52
	v_and_b32_e32 v52, 0xffff0000, v62
	v_fmac_f32_e32 v68, v26, v52
	v_lshlrev_b32_e32 v52, 16, v63
	v_fmac_f32_e32 v68, v25, v52
	v_and_b32_e32 v52, 0xffff0000, v63
	v_fmac_f32_e32 v68, v23, v52
	s_waitcnt lgkmcnt(0)
	v_lshlrev_b32_e32 v52, 16, v64
	v_fmac_f32_e32 v68, v21, v52
	v_and_b32_e32 v52, 0xffff0000, v64
	v_fmac_f32_e32 v68, v20, v52
	v_lshlrev_b32_e32 v52, 16, v65
	v_fmac_f32_e32 v68, v19, v52
	v_and_b32_e32 v52, 0xffff0000, v65
	v_fmac_f32_e32 v68, v18, v52
	v_lshlrev_b32_e32 v52, 16, v66
	v_fmac_f32_e32 v68, v17, v52
	v_and_b32_e32 v52, 0xffff0000, v66
	v_fmac_f32_e32 v68, v16, v52
	v_lshlrev_b32_e32 v52, 16, v67
	v_fmac_f32_e32 v68, v15, v52
	v_and_b32_e32 v52, 0xffff0000, v67
	v_fmac_f32_e32 v68, v14, v52
	s_nop 1
	v_add_f32_dpp v52, v68, v68 quad_perm:[1,0,3,2] row_mask:0xf bank_mask:0xf
	s_nop 1
	v_add_f32_dpp v53, v52, v52 quad_perm:[2,3,0,1] row_mask:0xf bank_mask:0xf
	s_nop 1
	v_add_f32_dpp v52, v53, v53 row_half_mirror row_mask:0xf bank_mask:0xf
	s_nop 1
	v_add_f32_dpp v53, v52, v52 row_mirror row_mask:0xf bank_mask:0xf
	v_mov_b32_e32 v52, v53
	s_nop 1
	v_permlane16_swap_b32_e32 v53, v52
	v_add_f32_e32 v53, v53, v52
	v_mov_b32_e32 v52, v53
	s_nop 1
	v_permlane32_swap_b32_e32 v53, v52
	ds_read_b128 v[54:57], v13 offset:16384
	ds_read_b128 v[58:61], v13 offset:16400
	ds_read_b128 v[62:65], v13 offset:16416
	ds_read_b128 v[66:69], v13 offset:16432
	s_waitcnt lgkmcnt(3)
	v_lshlrev_b32_e32 v70, 16, v54
	v_and_b32_e32 v54, 0xffff0000, v54
	v_fma_f32 v70, v47, v70, 0
	v_fmac_f32_e32 v70, v46, v54
	v_lshlrev_b32_e32 v54, 16, v55
	v_fmac_f32_e32 v70, v45, v54
	v_and_b32_e32 v54, 0xffff0000, v55
	v_fmac_f32_e32 v70, v44, v54
	v_lshlrev_b32_e32 v54, 16, v56
	v_fmac_f32_e32 v70, v43, v54
	v_and_b32_e32 v54, 0xffff0000, v56
	v_fmac_f32_e32 v70, v42, v54
	v_lshlrev_b32_e32 v54, 16, v57
	v_fmac_f32_e32 v70, v41, v54
	v_and_b32_e32 v54, 0xffff0000, v57
	v_fmac_f32_e32 v70, v40, v54
	s_waitcnt lgkmcnt(2)
	v_lshlrev_b32_e32 v54, 16, v58
	v_fmac_f32_e32 v70, v39, v54
	v_and_b32_e32 v54, 0xffff0000, v58
	v_fmac_f32_e32 v70, v38, v54
	v_lshlrev_b32_e32 v54, 16, v59
	v_fmac_f32_e32 v70, v37, v54
	v_and_b32_e32 v54, 0xffff0000, v59
	v_fmac_f32_e32 v70, v36, v54
	v_lshlrev_b32_e32 v54, 16, v60
	v_fmac_f32_e32 v70, v35, v54
	v_and_b32_e32 v54, 0xffff0000, v60
	v_fmac_f32_e32 v70, v34, v54
	v_lshlrev_b32_e32 v54, 16, v61
	v_fmac_f32_e32 v70, v33, v54
	v_and_b32_e32 v54, 0xffff0000, v61
	v_fmac_f32_e32 v70, v32, v54
	s_waitcnt lgkmcnt(1)
	v_lshlrev_b32_e32 v54, 16, v62
	v_fmac_f32_e32 v70, v31, v54
	v_and_b32_e32 v54, 0xffff0000, v62
	v_fmac_f32_e32 v70, v30, v54
	v_lshlrev_b32_e32 v54, 16, v63
	v_fmac_f32_e32 v70, v29, v54
	v_and_b32_e32 v54, 0xffff0000, v63
	v_fmac_f32_e32 v70, v28, v54
	v_lshlrev_b32_e32 v54, 16, v64
	v_fmac_f32_e32 v70, v27, v54
	v_and_b32_e32 v54, 0xffff0000, v64
	v_fmac_f32_e32 v70, v26, v54
	v_lshlrev_b32_e32 v54, 16, v65
	v_fmac_f32_e32 v70, v25, v54
	v_and_b32_e32 v54, 0xffff0000, v65
	v_fmac_f32_e32 v70, v23, v54
	s_waitcnt lgkmcnt(0)
	v_lshlrev_b32_e32 v54, 16, v66
	v_fmac_f32_e32 v70, v21, v54
	v_and_b32_e32 v54, 0xffff0000, v66
	v_fmac_f32_e32 v70, v20, v54
	v_lshlrev_b32_e32 v54, 16, v67
	v_fmac_f32_e32 v70, v19, v54
	v_and_b32_e32 v54, 0xffff0000, v67
	v_fmac_f32_e32 v70, v18, v54
	v_lshlrev_b32_e32 v54, 16, v68
	v_fmac_f32_e32 v70, v17, v54
	v_and_b32_e32 v54, 0xffff0000, v68
	v_fmac_f32_e32 v70, v16, v54
	v_lshlrev_b32_e32 v54, 16, v69
	v_fmac_f32_e32 v70, v15, v54
	v_and_b32_e32 v54, 0xffff0000, v69
	v_fmac_f32_e32 v70, v14, v54
	s_nop 1
	v_add_f32_dpp v54, v70, v70 quad_perm:[1,0,3,2] row_mask:0xf bank_mask:0xf
	s_nop 1
	v_add_f32_dpp v55, v54, v54 quad_perm:[2,3,0,1] row_mask:0xf bank_mask:0xf
	s_nop 1
	v_add_f32_dpp v54, v55, v55 row_half_mirror row_mask:0xf bank_mask:0xf
	s_nop 1
	v_add_f32_dpp v55, v54, v54 row_mirror row_mask:0xf bank_mask:0xf
	v_mov_b32_e32 v54, v55
	s_nop 1
	v_permlane16_swap_b32_e32 v55, v54
	v_add_f32_e32 v55, v55, v54
	v_mov_b32_e32 v54, v55
	s_nop 1
	v_permlane32_swap_b32_e32 v55, v54
	ds_read_b128 v[56:59], v13 offset:20480
	ds_read_b128 v[60:63], v13 offset:20496
	ds_read_b128 v[64:67], v13 offset:20512
	ds_read_b128 v[68:71], v13 offset:20528
	s_waitcnt lgkmcnt(3)
	v_lshlrev_b32_e32 v72, 16, v56
	v_and_b32_e32 v56, 0xffff0000, v56
	v_fma_f32 v72, v47, v72, 0
	v_fmac_f32_e32 v72, v46, v56
	v_lshlrev_b32_e32 v56, 16, v57
	v_fmac_f32_e32 v72, v45, v56
	v_and_b32_e32 v56, 0xffff0000, v57
	v_fmac_f32_e32 v72, v44, v56
	v_lshlrev_b32_e32 v56, 16, v58
	v_fmac_f32_e32 v72, v43, v56
	v_and_b32_e32 v56, 0xffff0000, v58
	v_fmac_f32_e32 v72, v42, v56
	v_lshlrev_b32_e32 v56, 16, v59
	v_fmac_f32_e32 v72, v41, v56
	v_and_b32_e32 v56, 0xffff0000, v59
	v_fmac_f32_e32 v72, v40, v56
	s_waitcnt lgkmcnt(2)
	v_lshlrev_b32_e32 v56, 16, v60
	v_fmac_f32_e32 v72, v39, v56
	v_and_b32_e32 v56, 0xffff0000, v60
	v_fmac_f32_e32 v72, v38, v56
	v_lshlrev_b32_e32 v56, 16, v61
	v_fmac_f32_e32 v72, v37, v56
	v_and_b32_e32 v56, 0xffff0000, v61
	v_fmac_f32_e32 v72, v36, v56
	v_lshlrev_b32_e32 v56, 16, v62
	v_fmac_f32_e32 v72, v35, v56
	v_and_b32_e32 v56, 0xffff0000, v62
	v_fmac_f32_e32 v72, v34, v56
	v_lshlrev_b32_e32 v56, 16, v63
	v_fmac_f32_e32 v72, v33, v56
	v_and_b32_e32 v56, 0xffff0000, v63
	v_fmac_f32_e32 v72, v32, v56
	s_waitcnt lgkmcnt(1)
; #define LAS __attribute__((address_space(3)))
; __device__ __forceinline__ void fl_rows(CPR P, LAS unsigned char* lds) {
;     ...
;         for (int j = 0; j < 8; ++j) {
;             float a = 0.f;
; #pragma unroll
;             for (int q = 0; q < 4; ++q) {
;                 const u32x4 w = *(const LAS u32x4*)(lds + j * 4096 + lane * 64 + q * 16);
; #pragma unroll
;                 for (int e = 0; e < 4; ++e) { a += xv[q * 8 + 2 * e] * __uint_as_float(w[e] << 16); a += xv[q * 8 + 2 * e + 1] * __uint_as_float(w[e] & 0xffff0000u); }
;             }
;             acc[j] = wsum(a);
;             __builtin_amdgcn_sched_barrier(0);
	v_lshlrev_b32_e32 v56, 16, v64
	v_fmac_f32_e32 v72, v31, v56
	v_and_b32_e32 v56, 0xffff0000, v64
	v_fmac_f32_e32 v72, v30, v56
	v_lshlrev_b32_e32 v56, 16, v65
	v_fmac_f32_e32 v72, v29, v56
	v_and_b32_e32 v56, 0xffff0000, v65
	v_fmac_f32_e32 v72, v28, v56
	v_lshlrev_b32_e32 v56, 16, v66
	v_fmac_f32_e32 v72, v27, v56
	v_and_b32_e32 v56, 0xffff0000, v66
	v_fmac_f32_e32 v72, v26, v56
	v_lshlrev_b32_e32 v56, 16, v67
	v_fmac_f32_e32 v72, v25, v56
	v_and_b32_e32 v56, 0xffff0000, v67
	v_fmac_f32_e32 v72, v23, v56
	s_waitcnt lgkmcnt(0)
	v_lshlrev_b32_e32 v56, 16, v68
	v_fmac_f32_e32 v72, v21, v56
	v_and_b32_e32 v56, 0xffff0000, v68
	v_fmac_f32_e32 v72, v20, v56
	v_lshlrev_b32_e32 v56, 16, v69
	v_fmac_f32_e32 v72, v19, v56
	v_and_b32_e32 v56, 0xffff0000, v69
	v_fmac_f32_e32 v72, v18, v56
	v_lshlrev_b32_e32 v56, 16, v70
	v_fmac_f32_e32 v72, v17, v56
	v_and_b32_e32 v56, 0xffff0000, v70
	v_fmac_f32_e32 v72, v16, v56
	v_lshlrev_b32_e32 v56, 16, v71
	v_fmac_f32_e32 v72, v15, v56
	v_and_b32_e32 v56, 0xffff0000, v71
	v_fmac_f32_e32 v72, v14, v56
	s_nop 1
	v_add_f32_dpp v56, v72, v72 quad_perm:[1,0,3,2] row_mask:0xf bank_mask:0xf
	s_nop 1
	v_add_f32_dpp v57, v56, v56 quad_perm:[2,3,0,1] row_mask:0xf bank_mask:0xf
	s_nop 1
	v_add_f32_dpp v56, v57, v57 row_half_mirror row_mask:0xf bank_mask:0xf
	s_nop 1
	v_add_f32_dpp v57, v56, v56 row_mirror row_mask:0xf bank_mask:0xf
	v_mov_b32_e32 v56, v57
	s_nop 1
	v_permlane16_swap_b32_e32 v57, v56
	v_add_f32_e32 v57, v57, v56
	v_mov_b32_e32 v56, v57
	s_nop 1
	v_permlane32_swap_b32_e32 v57, v56
	ds_read_b128 v[58:61], v13 offset:24576
	ds_read_b128 v[62:65], v13 offset:24592
	ds_read_b128 v[66:69], v13 offset:24608
	ds_read_b128 v[70:73], v13 offset:24624
	s_waitcnt lgkmcnt(3)
	v_lshlrev_b32_e32 v74, 16, v58
	v_and_b32_e32 v58, 0xffff0000, v58
	v_fma_f32 v74, v47, v74, 0
	v_fmac_f32_e32 v74, v46, v58
	v_lshlrev_b32_e32 v58, 16, v59
	v_fmac_f32_e32 v74, v45, v58
	v_and_b32_e32 v58, 0xffff0000, v59
	v_fmac_f32_e32 v74, v44, v58
	v_lshlrev_b32_e32 v58, 16, v60
	v_fmac_f32_e32 v74, v43, v58
	v_and_b32_e32 v58, 0xffff0000, v60
	v_fmac_f32_e32 v74, v42, v58
	v_lshlrev_b32_e32 v58, 16, v61
	v_fmac_f32_e32 v74, v41, v58
	v_and_b32_e32 v58, 0xffff0000, v61
	v_fmac_f32_e32 v74, v40, v58
	s_waitcnt lgkmcnt(2)
	v_lshlrev_b32_e32 v58, 16, v62
	v_fmac_f32_e32 v74, v39, v58
	v_and_b32_e32 v58, 0xffff0000, v62
	v_fmac_f32_e32 v74, v38, v58
	v_lshlrev_b32_e32 v58, 16, v63
	v_fmac_f32_e32 v74, v37, v58
	v_and_b32_e32 v58, 0xffff0000, v63
	v_fmac_f32_e32 v74, v36, v58
	v_lshlrev_b32_e32 v58, 16, v64
	v_fmac_f32_e32 v74, v35, v58
	v_and_b32_e32 v58, 0xffff0000, v64
	v_fmac_f32_e32 v74, v34, v58
	v_lshlrev_b32_e32 v58, 16, v65
	v_fmac_f32_e32 v74, v33, v58
	v_and_b32_e32 v58, 0xffff0000, v65
	v_fmac_f32_e32 v74, v32, v58
	s_waitcnt lgkmcnt(1)
	v_lshlrev_b32_e32 v58, 16, v66
	v_fmac_f32_e32 v74, v31, v58
	v_and_b32_e32 v58, 0xffff0000, v66
	v_fmac_f32_e32 v74, v30, v58
	v_lshlrev_b32_e32 v58, 16, v67
	v_fmac_f32_e32 v74, v29, v58
	v_and_b32_e32 v58, 0xffff0000, v67
	v_fmac_f32_e32 v74, v28, v58
	v_lshlrev_b32_e32 v58, 16, v68
	v_fmac_f32_e32 v74, v27, v58
	v_and_b32_e32 v58, 0xffff0000, v68
	v_fmac_f32_e32 v74, v26, v58
	v_lshlrev_b32_e32 v58, 16, v69
	v_fmac_f32_e32 v74, v25, v58
	v_and_b32_e32 v58, 0xffff0000, v69
	v_fmac_f32_e32 v74, v23, v58
	s_waitcnt lgkmcnt(0)
	v_lshlrev_b32_e32 v58, 16, v70
	v_fmac_f32_e32 v74, v21, v58
	v_and_b32_e32 v58, 0xffff0000, v70
	v_fmac_f32_e32 v74, v20, v58
	v_lshlrev_b32_e32 v58, 16, v71
	v_fmac_f32_e32 v74, v19, v58
	v_and_b32_e32 v58, 0xffff0000, v71
	v_fmac_f32_e32 v74, v18, v58
	v_lshlrev_b32_e32 v58, 16, v72
	v_fmac_f32_e32 v74, v17, v58
	v_and_b32_e32 v58, 0xffff0000, v72
	v_fmac_f32_e32 v74, v16, v58
	v_lshlrev_b32_e32 v58, 16, v73
	v_fmac_f32_e32 v74, v15, v58
	v_and_b32_e32 v58, 0xffff0000, v73
	v_fmac_f32_e32 v74, v14, v58
	s_nop 1
	v_add_f32_dpp v58, v74, v74 quad_perm:[1,0,3,2] row_mask:0xf bank_mask:0xf
	s_nop 1
	v_add_f32_dpp v59, v58, v58 quad_perm:[2,3,0,1] row_mask:0xf bank_mask:0xf
	s_nop 1
	v_add_f32_dpp v58, v59, v59 row_half_mirror row_mask:0xf bank_mask:0xf
	s_nop 1
	v_add_f32_dpp v59, v58, v58 row_mirror row_mask:0xf bank_mask:0xf
	v_mov_b32_e32 v58, v59
	s_nop 1
	v_permlane16_swap_b32_e32 v59, v58
	v_add_f32_e32 v59, v59, v58
	v_mov_b32_e32 v58, v59
	s_nop 1
	v_permlane32_swap_b32_e32 v59, v58
	ds_read_b128 v[60:63], v13 offset:28672
	ds_read_b128 v[64:67], v13 offset:28688
	ds_read_b128 v[68:71], v13 offset:28704
	ds_read_b128 v[72:75], v13 offset:28720
	s_waitcnt lgkmcnt(3)
; #define LAS __attribute__((address_space(3)))
; __device__ __forceinline__ void fl_rows(CPR P, LAS unsigned char* lds) {
;     ...
;         for (int j = 0; j < 8; ++j) {
;             float a = 0.f;
; #pragma unroll
;             for (int q = 0; q < 4; ++q) {
;                 const u32x4 w = *(const LAS u32x4*)(lds + j * 4096 + lane * 64 + q * 16);
; #pragma unroll
;                 for (int e = 0; e < 4; ++e) { a += xv[q * 8 + 2 * e] * __uint_as_float(w[e] << 16); a += xv[q * 8 + 2 * e + 1] * __uint_as_float(w[e] & 0xffff0000u); }
;             }
;             acc[j] = wsum(a);
;             __builtin_amdgcn_sched_barrier(0);
;         }
;         const float ri = ((const float*)(P.ws + WS_RINV))[row];
;         if (lane < 8) {
;             float v = acc[0];
; #pragma unroll
;             for (int j = 1; j < 8; ++j) v = (lane == j) ? acc[j] : v;
;             fl[(size_t)lane * S + row] = v * ri;
;         }
	v_lshlrev_b32_e32 v76, 16, v60
	v_and_b32_e32 v60, 0xffff0000, v60
	v_fma_f32 v47, v47, v76, 0
	v_fmac_f32_e32 v47, v46, v60
	v_lshlrev_b32_e32 v46, 16, v61
	v_fmac_f32_e32 v47, v45, v46
	v_and_b32_e32 v45, 0xffff0000, v61
	v_fmac_f32_e32 v47, v44, v45
	v_lshlrev_b32_e32 v44, 16, v62
	v_fmac_f32_e32 v47, v43, v44
	v_and_b32_e32 v43, 0xffff0000, v62
	v_fmac_f32_e32 v47, v42, v43
	v_lshlrev_b32_e32 v42, 16, v63
	v_fmac_f32_e32 v47, v41, v42
	v_and_b32_e32 v41, 0xffff0000, v63
	v_fmac_f32_e32 v47, v40, v41
	s_waitcnt lgkmcnt(2)
	v_lshlrev_b32_e32 v40, 16, v64
	v_fmac_f32_e32 v47, v39, v40
	v_and_b32_e32 v39, 0xffff0000, v64
	v_fmac_f32_e32 v47, v38, v39
	v_lshlrev_b32_e32 v38, 16, v65
	v_fmac_f32_e32 v47, v37, v38
	v_and_b32_e32 v37, 0xffff0000, v65
	v_fmac_f32_e32 v47, v36, v37
	v_lshlrev_b32_e32 v36, 16, v66
	v_fmac_f32_e32 v47, v35, v36
	v_and_b32_e32 v35, 0xffff0000, v66
	v_fmac_f32_e32 v47, v34, v35
	v_lshlrev_b32_e32 v34, 16, v67
	v_fmac_f32_e32 v47, v33, v34
	v_and_b32_e32 v33, 0xffff0000, v67
	v_fmac_f32_e32 v47, v32, v33
	s_waitcnt lgkmcnt(1)
	v_lshlrev_b32_e32 v32, 16, v68
	v_fmac_f32_e32 v47, v31, v32
	v_and_b32_e32 v31, 0xffff0000, v68
	v_fmac_f32_e32 v47, v30, v31
	v_lshlrev_b32_e32 v30, 16, v69
	v_fmac_f32_e32 v47, v29, v30
	v_and_b32_e32 v29, 0xffff0000, v69
	v_fmac_f32_e32 v47, v28, v29
	v_lshlrev_b32_e32 v28, 16, v70
	v_fmac_f32_e32 v47, v27, v28
	v_and_b32_e32 v27, 0xffff0000, v70
	v_fmac_f32_e32 v47, v26, v27
	v_lshlrev_b32_e32 v26, 16, v71
	v_fmac_f32_e32 v47, v25, v26
	v_and_b32_e32 v25, 0xffff0000, v71
	v_fmac_f32_e32 v47, v23, v25
	s_waitcnt lgkmcnt(0)
	v_lshlrev_b32_e32 v23, 16, v72
	v_fmac_f32_e32 v47, v21, v23
	v_and_b32_e32 v21, 0xffff0000, v72
	v_fmac_f32_e32 v47, v20, v21
	v_lshlrev_b32_e32 v20, 16, v73
	v_fmac_f32_e32 v47, v19, v20
	v_and_b32_e32 v19, 0xffff0000, v73
	v_fmac_f32_e32 v47, v18, v19
	v_lshlrev_b32_e32 v18, 16, v74
	v_fmac_f32_e32 v47, v17, v18
	v_and_b32_e32 v17, 0xffff0000, v74
	v_fmac_f32_e32 v47, v16, v17
	v_lshlrev_b32_e32 v16, 16, v75
	v_fmac_f32_e32 v47, v15, v16
	v_and_b32_e32 v15, 0xffff0000, v75
	v_fmac_f32_e32 v47, v14, v15
	s_nop 1
	v_add_f32_dpp v14, v47, v47 quad_perm:[1,0,3,2] row_mask:0xf bank_mask:0xf
	s_nop 1
	v_add_f32_dpp v15, v14, v14 quad_perm:[2,3,0,1] row_mask:0xf bank_mask:0xf
	s_nop 1
	v_add_f32_dpp v14, v15, v15 row_half_mirror row_mask:0xf bank_mask:0xf
	s_nop 1
	v_add_f32_dpp v15, v14, v14 row_mirror row_mask:0xf bank_mask:0xf
	v_mov_b32_e32 v14, v15
	s_nop 1
	v_permlane16_swap_b32_e32 v15, v14
	v_add_f32_e32 v15, v15, v14
	v_mov_b32_e32 v14, v15
	s_nop 1
	v_permlane32_swap_b32_e32 v15, v14
	s_and_saveexec_b64 s[18:19], vcc
	s_cbranch_execz .LBB0_822
	v_lshlrev_b64 v[16:17], 2, v[2:3]
	v_lshl_add_u64 v[18:19], s[22:23], 0, v[16:17]
	global_load_dword v3, v[18:19], off
	v_add_f32_e32 v23, v48, v49
	v_add_f32_e32 v22, v22, v24
	v_add_f32_e32 v21, v50, v51
	v_cndmask_b32_e64 v22, v22, v23, s[4:5]
	v_add_f32_e32 v20, v52, v53
	v_cndmask_b32_e64 v21, v22, v21, s[6:7]
	v_add_f32_e32 v19, v54, v55
	v_cndmask_b32_e64 v20, v21, v20, s[8:9]
	v_add_f32_e32 v18, v56, v57
	v_cndmask_b32_e64 v19, v20, v19, s[10:11]
	s_waitcnt lgkmcnt(0)
	v_add_f32_e32 v14, v14, v15
	v_add_f32_e32 v15, v58, v59
	v_cndmask_b32_e64 v18, v19, v18, s[12:13]
	v_cndmask_b32_e64 v15, v18, v15, s[14:15]
	v_cndmask_b32_e64 v14, v15, v14, s[16:17]
	s_waitcnt vmcnt(0)
	v_mul_f32_e32 v3, v14, v3
	v_lshl_add_u64 v[14:15], v[6:7], 0, v[16:17]
	global_store_dword v[14:15], v3, off
	s_branch .LBB0_822
